# P3: q-GEMM units dealt over 248 CUs so the 8 CUs taking the mem-KV GEMM unit get no q units (load balance)
# speedup vs baseline: 1.0588x; 1.0588x over previous
; #define PG8_STAGE(bufoff, gbase, voff) do { _Pragma("unroll") for (int _i = 0; _i < 2; ++_i) \
;         __builtin_amdgcn_global_load_lds((const unsigned*)((const char*)(gbase) + (voff)[_i]), (LAS unsigned*)(lds + (bufoff) + ldsw + _i * 8192), 16, 0, 0); } while (0)
; #define PG8_BAR __builtin_amdgcn_s_barrier()
;     __host__ __device__ bool next(int i, Unit& u) const {
;         const long L = (long)i * G + c; if (L >= nwg) return false;
;         int wgid = (int)L; { const int q = nwg / NXCD, r = nwg % NXCD, xcd = wgid % NXCD, off = wgid / NXCD; wgid = (xcd < r ? xcd * (q + 1) : r * (q + 1) + (xcd - r) * q) + off; }
;         const int nig = WGM * nN, gid = wgid / nig, fm = gid * WGM, gsz = (nM - fm) < WGM ? (nM - fm) : WGM;
;         u.pm = fm + ((wgid % nig) % gsz); u.pn = (wgid % nig) / gsz; return true;
; template <class Epi, bool ALIGN_EPI>
; __device__ __forceinline__ void gemm_phase(LAS unsigned char* lds, const Gemm g, const StaticOrder& S, const Epi& E) {
;     ...
;     for (int i = 0; i < 2; ++i) { int R, C; stage_rc(tid * 16 + i * 8192, R, C); const int Rb = Epi::PERM ? ((R & ~31) + perm32(R & 31)) : R;
;         voffA[i] = (unsigned)(R * g.lda + C) * 2u; voffB[i] = (unsigned)(Rb * g.ldb + C) * 2u; }
;     const size_t kstep = (size_t)(BK * 2);
;     const size_t hA = (size_t)HALF * g.lda * 2, hB = (size_t)HALF * g.ldb * 2;
;     const size_t tA = 2 * hA, tB = 2 * hB;
;     const unsigned ldsw = (unsigned)wid * 1024u;
;     const int aoff = lds_byte(wr * 64 + fr, fq * 8), boff = lds_byte(wc * 32 + fr, fq * 8);
;     ...
;     Unit cur, nxt; int ui = 0;
;     if (!S.next(0, cur)) return;
;     float rsv[8], rsn[8];
;     E.pre(cur, wr, fr, rsv); E.post(0, rsv);
;     f32x4 acc[2][2][4][2];
; #pragma unroll
;     for (int a = 0; a < 2; ++a)
; #pragma unroll
;         for (int b = 0; b < 2; ++b)
; #pragma unroll
;             for (int m = 0; m < 4; ++m)
; #pragma unroll
;                 for (int n = 0; n < 2; ++n) acc[a][b][m][n] = (f32x4){0.f, 0.f, 0.f, 0.f};
;     bf16x8 At[4][2], B0[2][2], B1[2][2];
;     const char* cA = (const char*)g.A + (size_t)cur.pm * tA + (size_t)cur.pn * g.acol; const char* cB = (const char*)g.Bt + (size_t)cur.pn * tB;
;     PG8_STAGE(PG8_SB(0, 0), cB, voffB); PG8_STAGE(PG8_SB(0, 1), cB + hB, voffB); PG8_STAGE(PG8_SA(0, 0), cA, voffA); PG8_STAGE(PG8_SA(0, 1), cA + hA, voffA);
;     if (wr == 1) PG8_BAR;
;     PG8_WAIT_V(2); PG8_BAR;
.LBB0_392:
	v_mov_b32_e32 v9, v193
	s_cmpk_gt_i32 s84, 0x23f
	s_nop 0
	v_readfirstlane_b32 s4, v9
	s_cbranch_scc1 .LBB0_410
	s_mov_b32 s100, s84
	s_cmp_lt_i32 s84, 64
	s_cbranch_scc1 .Lq_remap_done
	s_cmp_lt_i32 s84, 0x48
	s_cbranch_scc1 .LBB0_410
	s_sub_i32 s100, s84, 8
	s_sub_i32 s0, s0, 1
.Lq_remap_done:
	v_lshlrev_b32_e32 v0, 4, v9
	v_add_u32_e32 v1, 0x2000, v0
	v_ashrrev_i32_e32 v2, 31, v1
	v_lshrrev_b32_e32 v2, 22, v2
	v_add_u32_e32 v2, v1, v2
	v_ashrrev_i32_e32 v8, 10, v2
	v_mul_i32_i24_e32 v2, 0x400, v8
	v_sub_u32_e32 v1, v1, v2
	v_lshrrev_b32_e32 v2, 4, v1
	v_bitop3_b32 v1, v2, v1, 32 bitop3:0x6c
	v_ashrrev_i32_e32 v2, 31, v1
	v_lshrrev_b32_e32 v2, 26, v2
	v_add_u32_e32 v2, v1, v2
	v_lshlrev_b32_e32 v3, 3, v8
	s_waitcnt vmcnt(0)
	v_ashrrev_i32_e32 v10, 6, v2
	v_and_b32_e32 v3, -16, v3
	v_add_u32_e32 v3, v10, v3
	v_and_b32_e32 v4, 3, v10
	s_mov_b32 s14, 0xffffe0
	v_lshrrev_b32_e32 v5, 2, v3
	v_lshlrev_b32_e32 v6, 1, v3
	v_and_b32_e32 v2, 0xc0, v2
	v_and_or_b32 v4, v3, s14, v4
	v_and_b32_e32 v5, 4, v5
	v_and_b32_e32 v6, 24, v6
	v_sub_u32_e32 v1, v1, v2
	v_mov_b32_e32 v2, 1
	s_ashr_i32 s16, s4, 6
	v_or3_b32 v4, v4, v5, v6
	v_lshlrev_b32_e32 v5, 5, v8
	v_ashrrev_i16_sdwa v1, v2, sext(v1) dst_sel:DWORD dst_unused:UNUSED_PAD src0_sel:DWORD src1_sel:BYTE_0
	s_ashr_i32 s5, s4, 8
	s_lshl_b32 s2, s16, 10
	v_and_b32_e32 v5, 32, v5
	v_bfe_i32 v11, v1, 0, 16
	s_add_u32 s3, s10, 0x900000
	v_mul_u32_u24_e32 v4, 0x300, v4
	v_add_u32_e32 v1, v5, v11
	v_lshlrev_b32_e32 v3, 12, v3
	s_addc_u32 s36, s11, 0
	v_add_lshl_u32 v128, v4, v1, 1
	v_lshl_add_u32 v130, v1, 1, v3
	v_bfe_i32 v1, v9, 27, 1
	s_add_u32 s37, s10, 0x10000000
	v_lshrrev_b32_e32 v1, 22, v1
	s_addc_u32 s38, s11, 0
	v_add_u32_e32 v1, v0, v1
	v_and_b32_e32 v1, 0xfffffc00, v1
	s_movk_i32 s39, 0x49
	s_and_b64 s[6:7], s[6:7], exec
	v_sub_u32_e32 v0, v0, v1
	s_cselect_b32 s6, s39, 0x48
	v_lshrrev_b32_e32 v1, 4, v0
	s_mul_i32 s1, s1, s6
	v_bitop3_b32 v1, v1, v0, 32 bitop3:0x6c
	v_ashrrev_i32_e32 v0, 31, v0
	s_add_i32 s1, s1, s0
	v_lshrrev_b32_e32 v0, 26, v0
	s_mul_hi_i32 s0, s1, 0x38e38e39
	v_add_u32_e32 v0, v1, v0
	s_lshr_b32 s6, s0, 31
	s_ashr_i32 s0, s0, 3
	v_ashrrev_i32_e32 v12, 6, v0
	v_ashrrev_i32_e32 v0, 31, v9
	s_add_i32 s0, s0, s6
	v_lshrrev_b32_e32 v0, 26, v0
	s_lshl_b32 s7, s0, 2
	s_mul_i32 s0, s0, 36
	v_add_u32_e32 v0, v9, v0
	s_sub_i32 s0, s1, s0
	v_ashrrev_i32_e32 v13, 6, v0
	s_bfe_i32 s1, s0, 0x80000
	v_lshlrev_b32_e32 v0, 3, v13
	s_bfe_u32 s1, s1, 0x2000d
	v_and_b32_e32 v0, -16, v0
	s_add_i32 s1, s0, s1
	v_add_u32_e32 v0, v12, v0
	s_bfe_i32 s6, s1, 0x80000
	s_and_b32 s1, s1, 0xfc
	v_and_b32_e32 v3, 3, v12
	v_lshrrev_b32_e32 v4, 2, v0
	v_lshlrev_b32_e32 v5, 1, v0
	s_sub_i32 s0, s0, s1
	v_and_or_b32 v3, v0, s14, v3
	v_and_b32_e32 v4, 4, v4
	v_and_b32_e32 v5, 24, v5
	s_sext_i32_i8 s0, s0
	v_or3_b32 v3, v3, v4, v5
	v_mul_i32_i24_e32 v5, 64, v12
	s_sext_i32_i16 s17, s6
	s_add_i32 s28, s7, s0
	v_sub_u32_e32 v1, v1, v5
	s_ashr_i32 s29, s28, 31
	s_ashr_i32 s0, s17, 2
	v_lshlrev_b32_e32 v4, 5, v13
	v_ashrrev_i16_sdwa v1, v2, sext(v1) dst_sel:DWORD dst_unused:UNUSED_PAD src0_sel:DWORD src1_sel:BYTE_0
	s_lshr_b32 s6, s17, 2
	s_lshl_b64 s[14:15], s[28:29], 20
	s_mul_hi_i32 s1, s0, 0x60000
	s_mul_i32 s0, s0, 0x60000
	v_and_b32_e32 v4, 32, v4
	v_bfe_i32 v14, v1, 0, 16
	s_add_u32 s30, s3, s0
	v_mul_u32_u24_e32 v3, 0x300, v3
	v_add_u32_e32 v1, v4, v14
	s_addc_u32 s31, s36, s1
	s_add_i32 s0, s2, 0
	v_add_lshl_u32 v132, v3, v1, 1
	s_add_i32 m0, s0, 0x10000
	v_lshlrev_b32_e32 v0, 12, v0
	global_load_lds_dwordx4 v132, s[30:31]
	s_add_i32 m0, s0, 0x12000
	s_add_u32 s18, s30, 0x30000
	global_load_lds_dwordx4 v128, s[30:31]
	s_addc_u32 s19, s31, 0
	s_add_i32 m0, s0, 0x14000
	v_lshl_add_u32 v134, v1, 1, v0
	global_load_lds_dwordx4 v132, s[18:19]
	s_add_i32 m0, s0, 0x16000
	s_add_u32 s34, s37, s14
	s_addc_u32 s35, s38, s15
	s_add_i32 s1, s0, 0x2000
	global_load_lds_dwordx4 v128, s[18:19]
	s_mov_b32 m0, s0
	s_add_u32 s14, s34, 0x80000
	global_load_lds_dwordx4 v134, s[34:35]
	s_mov_b32 m0, s1
	s_addc_u32 s15, s35, 0
	s_add_i32 s29, s0, 0x4000
	global_load_lds_dwordx4 v130, s[34:35]
	s_mov_b32 m0, s29
	s_add_i32 s40, s0, 0x6000
	global_load_lds_dwordx4 v134, s[14:15]
	s_mov_b32 m0, s40
	v_mov_b32_e32 v133, 0
	global_load_lds_dwordx4 v130, s[14:15]
	v_mov_b32_e32 v129, v133
	v_mov_b32_e32 v135, v133
	v_mov_b32_e32 v131, v133
	s_cmp_eq_u32 s5, 1
	s_mov_b32 s41, 0
	v_lshl_add_u64 v[6:7], s[30:31], 0, v[132:133]
	v_lshl_add_u64 v[4:5], s[30:31], 0, v[128:129]
	v_lshl_add_u64 v[0:1], s[34:35], 0, v[134:135]
	s_cselect_b64 s[14:15], -1, 0
	s_cmp_lg_u32 s5, 1
	v_lshl_add_u64 v[2:3], s[34:35], 0, v[130:131]
	s_cbranch_scc1 .LBB0_395
	s_barrier

;     __host__ __device__ bool next(int i, Unit& u) const {
;         const long L = (long)i * G + c; if (L >= nwg) return false;
;         int wgid = (int)L; { const int q = nwg / NXCD, r = nwg % NXCD, xcd = wgid % NXCD, off = wgid / NXCD; wgid = (xcd < r ? xcd * (q + 1) : r * (q + 1) + (xcd - r) * q) + off; }
;         const int nig = WGM * nN, gid = wgid / nig, fm = gid * WGM, gsz = (nM - fm) < WGM ? (nM - fm) : WGM;
;         u.pm = fm + ((wgid % nig) % gsz); u.pn = (wgid % nig) / gsz; return true;
; template <class Epi, bool ALIGN_EPI>
; __device__ __forceinline__ void gemm_phase(LAS unsigned char* lds, const Gemm g, const StaticOrder& S, const Epi& E) {
;     ...
;         const bool has_next = S.next(ui + 1, nxt);
;         const char* nA = has_next ? (const char*)g.A + (size_t)nxt.pm * tA + (size_t)nxt.pn * g.acol : cA; const char* nB = has_next ? (const char*)g.Bt + (size_t)nxt.pn * tB : cB;
.LBB0_398:
	s_add_i32 s41, s41, 1
	s_mul_i32 s4, s41, 0xf8
	s_add_u32 s4, s4, s100
	s_mov_b32 s5, 0
	v_cmp_gt_i64_e32 vcc, s[4:5], v[142:143]
	v_cmp_lt_i64_e64 s[6:7], s[4:5], v[140:141]
	s_cbranch_vccnz .LBB0_400
	s_ashr_i32 s5, s4, 31
	s_lshr_b32 s5, s5, 29
	s_add_i32 s5, s4, s5
	s_ashr_i32 s22, s5, 3
	s_and_b32 s5, s5, -8
	s_sub_i32 s4, s4, s5
	s_cmp_lt_i32 s4, 0
	s_cselect_b32 s5, s39, 0x48
	s_mul_i32 s4, s4, s5
	s_add_i32 s4, s4, s22
	s_mul_hi_i32 s5, s4, 0x38e38e39
	s_lshr_b32 s22, s5, 31
	s_ashr_i32 s5, s5, 3
	s_add_i32 s5, s5, s22
	s_lshl_b32 s22, s5, 2
	s_sub_i32 s23, 64, s22
	s_min_i32 s23, s23, 4
	s_abs_i32 s24, s23
	v_cvt_f32_u32_e32 v0, s24
	s_sub_i32 s26, 0, s24
	s_mul_i32 s5, s5, 36
	s_sub_i32 s4, s4, s5
	v_rcp_iflag_f32_e32 v0, v0
	s_abs_i32 s5, s4
	s_xor_b32 s25, s4, s23
	s_ashr_i32 s25, s25, 31
	v_mul_f32_e32 v0, 0x4f7ffffe, v0
	v_cvt_u32_f32_e32 v0, v0
	s_nop 0
	v_readfirstlane_b32 s27, v0
	s_mul_i32 s26, s26, s27
	s_mul_hi_u32 s26, s27, s26
	s_add_i32 s27, s27, s26
	s_mul_hi_u32 s26, s5, s27
	s_mul_i32 s27, s26, s24
	s_sub_i32 s5, s5, s27
	s_add_i32 s48, s26, 1
	s_sub_i32 s27, s5, s24
	s_cmp_ge_u32 s5, s24
	s_cselect_b32 s26, s48, s26
	s_cselect_b32 s5, s27, s5
	s_add_i32 s27, s26, 1
	s_cmp_ge_u32 s5, s24
	s_cselect_b32 s5, s27, s26
	s_xor_b32 s5, s5, s25
	s_sub_i32 s48, s5, s25
	s_mul_i32 s5, s48, s23
	s_sub_i32 s4, s4, s5
	s_add_i32 s22, s22, s4

; #define LAS __attribute__((address_space(3)))
; __global__ void __launch_bounds__(512, 2) fwd_kernel(Params p) {
;     extern __shared__ __attribute__((aligned(16))) unsigned char lds_raw[];
;     LAS unsigned char* lds = (LAS unsigned char*)lds_raw;
	.amdhsa_kernel _Z10fwd_kernel6Params
		.amdhsa_group_segment_fixed_size 0
		.amdhsa_private_segment_fixed_size 0
		.amdhsa_kernarg_size 496
		.amdhsa_user_sgpr_count 2
		.amdhsa_user_sgpr_dispatch_ptr 0
		.amdhsa_user_sgpr_queue_ptr 0
		.amdhsa_user_sgpr_kernarg_segment_ptr 1
		.amdhsa_user_sgpr_dispatch_id 0
		.amdhsa_user_sgpr_kernarg_preload_length 0
		.amdhsa_user_sgpr_kernarg_preload_offset 0
		.amdhsa_user_sgpr_private_segment_size 0
		.amdhsa_uses_dynamic_stack 0
		.amdhsa_enable_private_segment 0
		.amdhsa_system_sgpr_workgroup_id_x 1
		.amdhsa_system_sgpr_workgroup_id_y 0
		.amdhsa_system_sgpr_workgroup_id_z 0
		.amdhsa_system_sgpr_workgroup_info 0
		.amdhsa_system_vgpr_workitem_id 2
		.amdhsa_next_free_vgpr 251
		.amdhsa_next_free_sgpr 102
		.amdhsa_accum_offset 252
		.amdhsa_reserve_vcc 1
		.amdhsa_float_round_mode_32 0
		.amdhsa_float_round_mode_16_64 0
		.amdhsa_float_denorm_mode_32 3
		.amdhsa_float_denorm_mode_16_64 3
		.amdhsa_dx10_clamp 1
		.amdhsa_ieee_mode 1
		.amdhsa_fp16_overflow 0
		.amdhsa_tg_split 0
		.amdhsa_exception_fp_ieee_invalid_op 0
		.amdhsa_exception_fp_denorm_src 0
		.amdhsa_exception_fp_ieee_div_zero 0
		.amdhsa_exception_fp_ieee_overflow 0
		.amdhsa_exception_fp_ieee_underflow 0
		.amdhsa_exception_fp_ieee_inexact 0
		.amdhsa_exception_int_div_zero 0
	.end_amdhsa_kernel

; #define LAS __attribute__((address_space(3)))
; __global__ void __launch_bounds__(512, 2) fwd_kernel(Params p) {
;     extern __shared__ __attribute__((aligned(16))) unsigned char lds_raw[];
;     LAS unsigned char* lds = (LAS unsigned char*)lds_raw;
amdhsa.kernels:
  - .agpr_count:     0
    .args:
      - .offset:         0
        .size:           240
        .value_kind:     by_value
      - .offset:         240
        .size:           4
        .value_kind:     hidden_block_count_x
      - .offset:         244
        .size:           4
        .value_kind:     hidden_block_count_y
      - .offset:         248
        .size:           4
        .value_kind:     hidden_block_count_z
      - .offset:         252
        .size:           2
        .value_kind:     hidden_group_size_x
      - .offset:         254
        .size:           2
        .value_kind:     hidden_group_size_y
      - .offset:         256
        .size:           2
        .value_kind:     hidden_group_size_z
      - .offset:         258
        .size:           2
        .value_kind:     hidden_remainder_x
      - .offset:         260
        .size:           2
        .value_kind:     hidden_remainder_y
      - .offset:         262
        .size:           2
        .value_kind:     hidden_remainder_z
      - .offset:         280
        .size:           8
        .value_kind:     hidden_global_offset_x
      - .offset:         288
        .size:           8
        .value_kind:     hidden_global_offset_y
      - .offset:         296
        .size:           8
        .value_kind:     hidden_global_offset_z
      - .offset:         304
        .size:           2
        .value_kind:     hidden_grid_dims
      - .offset:         328
        .size:           8
        .value_kind:     hidden_multigrid_sync_arg
      - .offset:         360
        .size:           4
        .value_kind:     hidden_dynamic_lds_size
    .group_segment_fixed_size: 0
    .kernarg_segment_align: 8
    .kernarg_segment_size: 496
    .language:       OpenCL C
    .language_version:
      - 2
      - 0
    .max_flat_workgroup_size: 512
    .name:           _Z10fwd_kernel6Params
    .private_segment_fixed_size: 0
    .sgpr_count:     108
    .sgpr_spill_count: 17
    .symbol:         _Z10fwd_kernel6Params.kd
    .uniform_work_group_size: 1
    .uses_dynamic_stack: false
    .vgpr_count:     251
    .vgpr_spill_count: 0
    .wavefront_size: 64
